# grid barrier: non-leader workgroups issue their L1 invalidate right after arriving (CU idle until release) instead of after the release; XCD leader keeps post-release invalidate
# baseline (speedup 1.0000x reference)
.LBB0_140:
	s_or_b64 exec, exec, s[8:9]
	v_cvt_f32_u32_e32 v4, v2
	s_waitcnt vmcnt(0)
	v_readfirstlane_b32 s3, v3
	v_sub_u32_e32 v3, 0, v2
	v_rcp_iflag_f32_e32 v4, v4
	v_add_u32_e32 v5, s3, v1
	v_mul_f32_e32 v4, 0x4f7ffffe, v4
	v_cvt_u32_f32_e32 v4, v4
	v_mul_lo_u32 v1, v3, v4
	v_mul_hi_u32 v1, v4, v1
	v_add_u32_e32 v1, v4, v1
	v_mul_hi_u32 v1, v5, v1
	v_mul_lo_u32 v3, v1, v2
	v_sub_u32_e32 v3, v5, v3
	v_add_u32_e32 v4, 1, v1
	v_cmp_ge_u32_e32 vcc, v3, v2
	s_nop 1
	v_cndmask_b32_e32 v1, v1, v4, vcc
	v_sub_u32_e32 v4, v3, v2
	v_cndmask_b32_e32 v3, v3, v4, vcc
	v_add_u32_e32 v4, 1, v1
	v_cmp_ge_u32_e32 vcc, v3, v2
	v_add_u32_e32 v3, 1, v5
	s_nop 0
	v_cndmask_b32_e32 v1, v1, v4, vcc
	v_mul_lo_u32 v4, v2, v1
	v_add_u32_e32 v2, v4, v2
	v_cmp_ne_u32_e32 vcc, v3, v2
	s_and_saveexec_b64 s[6:7], vcc
	s_xor_b64 s[6:7], exec, s[6:7]
	s_cbranch_execz .LBB0_154
	s_waitcnt lgkmcnt(0)
	v_mov_b32_e32 v0, 0x2000
	buffer_inv sc1
	global_load_dword v0, v0, s[4:5] offset:1024 sc1
	s_add_u32 s12, s4, 0x2400
	s_addc_u32 s13, s5, 0
	s_waitcnt vmcnt(0)
	v_cmp_eq_u32_e32 vcc, v0, v1
	s_and_saveexec_b64 s[8:9], vcc
	s_cbranch_execz .LBB0_153
	s_add_u32 s10, s24, 0x28100200
	s_addc_u32 s11, s25, 0
	s_mov_b32 s3, 1
	s_mov_b64 s[14:15], 0
	v_mov_b32_e32 v0, 0
	s_branch .LBB0_144

.LBB0_153:
	s_or_b64 exec, exec, s[8:9]
	s_waitcnt vmcnt(0)
	s_waitcnt vmcnt(0)

.LBB0_939:
	s_or_b64 exec, exec, s[16:17]
	v_cvt_f32_u32_e32 v4, v2
	s_waitcnt vmcnt(0)
	v_readfirstlane_b32 s2, v3
	v_sub_u32_e32 v3, 0, v2
	v_rcp_iflag_f32_e32 v4, v4
	v_add_u32_e32 v5, s2, v1
	v_mul_f32_e32 v4, 0x4f7ffffe, v4
	v_cvt_u32_f32_e32 v4, v4
	v_mul_lo_u32 v1, v3, v4
	v_mul_hi_u32 v1, v4, v1
	v_add_u32_e32 v1, v4, v1
	v_mul_hi_u32 v1, v5, v1
	v_mul_lo_u32 v3, v1, v2
	v_sub_u32_e32 v3, v5, v3
	v_add_u32_e32 v4, 1, v1
	v_cmp_ge_u32_e32 vcc, v3, v2
	s_nop 1
	v_cndmask_b32_e32 v1, v1, v4, vcc
	v_sub_u32_e32 v4, v3, v2
	v_cndmask_b32_e32 v3, v3, v4, vcc
	v_add_u32_e32 v4, 1, v1
	v_cmp_ge_u32_e32 vcc, v3, v2
	v_add_u32_e32 v3, 1, v5
	s_nop 0
	v_cndmask_b32_e32 v1, v1, v4, vcc
	v_mul_lo_u32 v4, v2, v1
	v_add_u32_e32 v2, v4, v2
	v_cmp_ne_u32_e32 vcc, v3, v2
	s_and_saveexec_b64 s[8:9], vcc
	s_xor_b64 s[14:15], exec, s[8:9]
	s_cbranch_execz .LBB0_953
	s_waitcnt lgkmcnt(0)
	buffer_inv sc1
	global_load_dword v0, v223, s[12:13] offset:1024 sc1
	s_add_u32 s18, s12, 0x2400
	s_addc_u32 s19, s13, 0
	s_waitcnt vmcnt(0)
	v_cmp_eq_u32_e32 vcc, v0, v1
	s_and_saveexec_b64 s[16:17], vcc
	s_cbranch_execz .LBB0_952
	s_mov_b32 s2, 1
	s_mov_b64 s[20:21], 0
	s_branch .LBB0_943

.LBB0_952:
	s_or_b64 exec, exec, s[16:17]
	s_waitcnt vmcnt(0)
	s_waitcnt vmcnt(0)

.LBB0_1593:
	s_or_b64 exec, exec, s[18:19]
	v_cvt_f32_u32_e32 v4, v2
	s_waitcnt vmcnt(0)
	v_readfirstlane_b32 s2, v3
	v_sub_u32_e32 v3, 0, v2
	v_rcp_iflag_f32_e32 v4, v4
	v_add_u32_e32 v5, s2, v1
	v_mul_f32_e32 v4, 0x4f7ffffe, v4
	v_cvt_u32_f32_e32 v4, v4
	v_mul_lo_u32 v1, v3, v4
	v_mul_hi_u32 v1, v4, v1
	v_add_u32_e32 v1, v4, v1
	v_mul_hi_u32 v1, v5, v1
	v_mul_lo_u32 v3, v1, v2
	v_sub_u32_e32 v3, v5, v3
	v_add_u32_e32 v4, 1, v1
	v_cmp_ge_u32_e32 vcc, v3, v2
	s_nop 1
	v_cndmask_b32_e32 v1, v1, v4, vcc
	v_sub_u32_e32 v4, v3, v2
	v_cndmask_b32_e32 v3, v3, v4, vcc
	v_add_u32_e32 v4, 1, v1
	v_cmp_ge_u32_e32 vcc, v3, v2
	v_add_u32_e32 v3, 1, v5
	s_nop 0
	v_cndmask_b32_e32 v1, v1, v4, vcc
	v_mul_lo_u32 v4, v2, v1
	v_add_u32_e32 v2, v4, v2
	v_cmp_ne_u32_e32 vcc, v3, v2
	s_and_saveexec_b64 s[8:9], vcc
	s_xor_b64 s[16:17], exec, s[8:9]
	s_cbranch_execz .LBB0_1607
	s_waitcnt lgkmcnt(0)
	buffer_inv sc1
	global_load_dword v0, v223, s[14:15] offset:1024 sc1
	s_add_u32 s20, s14, 0x2400
	s_addc_u32 s21, s15, 0
	s_waitcnt vmcnt(0)
	v_cmp_eq_u32_e32 vcc, v0, v1
	s_and_saveexec_b64 s[18:19], vcc
	s_cbranch_execz .LBB0_1606
	s_mov_b32 s2, 1
	s_mov_b64 s[30:31], 0
	s_branch .LBB0_1597

.LBB0_1606:
	s_or_b64 exec, exec, s[18:19]
	s_waitcnt vmcnt(0)
	s_waitcnt vmcnt(0)

.LBB0_1713:
	s_or_b64 exec, exec, s[16:17]
	v_cvt_f32_u32_e32 v4, v2
	s_waitcnt vmcnt(0)
	v_readfirstlane_b32 s8, v3
	v_sub_u32_e32 v3, 0, v2
	v_rcp_iflag_f32_e32 v4, v4
	v_add_u32_e32 v5, s8, v1
	v_mul_f32_e32 v4, 0x4f7ffffe, v4
	v_cvt_u32_f32_e32 v4, v4
	v_mul_lo_u32 v1, v3, v4
	v_mul_hi_u32 v1, v4, v1
	v_add_u32_e32 v1, v4, v1
	v_mul_hi_u32 v1, v5, v1
	v_mul_lo_u32 v3, v1, v2
	v_sub_u32_e32 v3, v5, v3
	v_add_u32_e32 v4, 1, v1
	v_cmp_ge_u32_e32 vcc, v3, v2
	s_nop 1
	v_cndmask_b32_e32 v1, v1, v4, vcc
	v_sub_u32_e32 v4, v3, v2
	v_cndmask_b32_e32 v3, v3, v4, vcc
	v_add_u32_e32 v4, 1, v1
	v_cmp_ge_u32_e32 vcc, v3, v2
	v_add_u32_e32 v3, 1, v5
	s_nop 0
	v_cndmask_b32_e32 v1, v1, v4, vcc
	v_mul_lo_u32 v4, v2, v1
	v_add_u32_e32 v2, v4, v2
	v_cmp_ne_u32_e32 vcc, v3, v2
	s_and_saveexec_b64 s[8:9], vcc
	s_xor_b64 s[14:15], exec, s[8:9]
	s_cbranch_execz .LBB0_1727
	s_waitcnt lgkmcnt(0)
	buffer_inv sc1
	global_load_dword v0, v223, s[12:13] offset:1024 sc1
	s_add_u32 s18, s12, 0x2400
	s_addc_u32 s19, s13, 0
	s_waitcnt vmcnt(0)
	v_cmp_eq_u32_e32 vcc, v0, v1
	s_and_saveexec_b64 s[16:17], vcc
	s_cbranch_execz .LBB0_1726
	s_mov_b32 s8, 1
	s_mov_b64 s[20:21], 0
	s_branch .LBB0_1717
